# phase-3 conv loop: 8-deep row prefetch ring (unrolled x8) instead of one exposed load per token; plus p10/p12 epilogue load hoists
# speedup vs baseline: 1.0163x; 1.0163x over previous
; __device__ __forceinline__ void unpack8(const u32x4 r, float (&o)[8]) { o[0] = bflo(r.x); o[1] = bfhi(r.x); o[2] = bflo(r.y); o[3] = bfhi(r.y); o[4] = bflo(r.z); o[5] = bfhi(r.z); o[6] = bflo(r.w); o[7] = bfhi(r.w); }
; __device__ __forceinline__ u32x4 pack8(const float (&o)[8]) { u32x4 r; r.x = pk2(o[0], o[1]); r.y = pk2(o[2], o[3]); r.z = pk2(o[4], o[5]); r.w = pk2(o[6], o[7]); return r; }
; __device__ __forceinline__ float siluf_(float x) { return x * __builtin_amdgcn_rcpf(1.0f + __expf(-x)); }
; __device__ __forceinline__ void phase_conv_pool(const Params& p, unsigned char* smem) {
;     ...
;         const int col = tid * 8, tpb = (MLAT + (int)gridDim.x - 1) / (int)gridDim.x, t0 = blockIdx.x * tpb, t1 = min(t0 + tpb, MLAT);
;         float w0[8], w1[8], w2[8], bb[8]; load8f(cw + col, w0); load8f(cw + 4096 + col, w1); load8f(cw + 8192 + col, w2); load8f(cb + col, bb);
;         if (t0 < t1) {
;             const bf16_t* src = raw + (size_t)t0 * 4096 + col; bf16_t* dst = xcl + (size_t)t0 * 4096 + col;
;             float x0[8], x1[8];
;             unpack8(((t0 & (SEQ - 1)) != 0) ? *(const u32x4*)(src - 4096) : zero, x0); unpack8(*(const u32x4*)src, x1);
; #pragma unroll 4
;             for (int t = t0; t < t1; ++t) {
;                 const u32x4 r2 = (((t + 1) & (SEQ - 1)) != 0) ? __builtin_nontemporal_load((const u32x4*)(src + 4096)) : zero;
;                 float x2[8], o[8]; unpack8(r2, x2);
; #pragma unroll
;                 for (int e = 0; e < 8; ++e) o[e] = siluf_(x0[e] * w0[e] + bb[e] + x1[e] * w1[e] + x2[e] * w2[e]);
;                 *(u32x4*)dst = pack8(o);
; #pragma unroll
;                 for (int e = 0; e < 8; ++e) { x0[e] = x1[e]; x1[e] = x2[e]; }
;                 src += 4096; dst += 4096;
;             }
;         }
.LBB0_318:
	global_load_dwordx4 v[52:55], v[38:39], off
	s_lshl_b64 s[10:11], s[10:11], 1
	s_add_u32 s10, s82, s10
	s_addc_u32 s11, s83, s11
	v_mov_b32_e32 v41, 0
	s_add_u32 s8, s84, s8
	v_lshl_add_u64 v[38:39], s[10:11], 0, v[40:41]
	v_lshlrev_b32_e32 v40, 4, v154
	s_addc_u32 s9, s85, s9
	s_waitcnt vmcnt(0)
	v_and_b32_e32 v58, 0xffff0000, v37
	v_lshlrev_b32_e32 v59, 16, v37
	v_and_b32_e32 v60, 0xffff0000, v36
	v_lshlrev_b32_e32 v61, 16, v36
	v_mov_b32_e32 v36, v26
	v_mov_b32_e32 v37, v6
	v_mov_b32_e32 v6, v27
	s_mov_b64 s[14:15], 0x6892000
	v_lshl_add_u64 v[26:27], s[8:9], 0, v[40:41]
	v_and_b32_e32 v62, 0xffff0000, v35
	v_lshlrev_b32_e32 v63, 16, v35
	v_and_b32_e32 v64, 0xffff0000, v34
	v_lshlrev_b32_e32 v65, 16, v34
	v_mov_b32_e32 v34, v32
	v_mov_b32_e32 v35, v4
	v_mov_b32_e32 v4, v33
	v_mov_b32_e32 v32, v30
	v_mov_b32_e32 v33, v2
	v_mov_b32_e32 v2, v31
	v_mov_b32_e32 v30, v28
	v_mov_b32_e32 v31, v8
	v_mov_b32_e32 v8, v29
	v_lshl_add_u64 v[40:41], v[26:27], 0, s[14:15]
	s_mov_b64 s[8:9], 0x2000
	v_and_b32_e32 v43, 0xffff0000, v55
	v_lshlrev_b32_e32 v45, 16, v55
	v_and_b32_e32 v47, 0xffff0000, v54
	v_lshlrev_b32_e32 v49, 16, v54
	v_and_b32_e32 v51, 0xffff0000, v53
	v_lshlrev_b32_e32 v53, 16, v53
	v_and_b32_e32 v55, 0xffff0000, v52
	v_lshlrev_b32_e32 v57, 16, v52
	global_load_dwordx4 v[100:103], v[40:41], off nt
	v_lshl_add_u64 v[40:41], v[40:41], 0, s[8:9]
	global_load_dwordx4 v[104:107], v[40:41], off nt
	v_lshl_add_u64 v[40:41], v[40:41], 0, s[8:9]
	global_load_dwordx4 v[108:111], v[40:41], off nt
	v_lshl_add_u64 v[40:41], v[40:41], 0, s[8:9]
	global_load_dwordx4 v[112:115], v[40:41], off nt
	v_lshl_add_u64 v[40:41], v[40:41], 0, s[8:9]
	global_load_dwordx4 v[116:119], v[40:41], off nt
	v_lshl_add_u64 v[40:41], v[40:41], 0, s[8:9]
	global_load_dwordx4 v[120:123], v[40:41], off nt
	v_lshl_add_u64 v[40:41], v[40:41], 0, s[8:9]
	global_load_dwordx4 v[124:127], v[40:41], off nt
	v_lshl_add_u64 v[40:41], v[40:41], 0, s[8:9]
	global_load_dwordx4 v[128:131], v[40:41], off nt
	v_lshl_add_u64 v[40:41], v[40:41], 0, s[8:9]
.Lcv3_0:
	s_add_i32 s6, s6, 1
	s_and_b32 s7, s6, 0xfff
	v_mov_b32_e32 v42, v43
	v_mov_b32_e32 v44, v45
	v_mov_b32_e32 v46, v47
	v_mov_b32_e32 v48, v49
	v_mov_b32_e32 v50, v51
	v_mov_b32_e32 v52, v53
	v_mov_b32_e32 v54, v55
	v_mov_b32_e32 v56, v57
	s_cmp_eq_u32 s7, 0
	s_waitcnt vmcnt(7)
	s_cbranch_scc0 .Lcv3_go_0
	v_mov_b32_e32 v100, 0
	v_mov_b32_e32 v101, 0
	v_mov_b32_e32 v102, 0
	v_mov_b32_e32 v103, 0
.Lcv3_go_0:
	v_lshlrev_b32_e32 v57, 16, v100
	v_and_b32_e32 v55, 0xffff0000, v100
	v_lshlrev_b32_e32 v53, 16, v101
	v_and_b32_e32 v51, 0xffff0000, v101
	v_fma_f32 v43, v18, v65, v22
	v_pk_mul_f32 v[26:27], v[36:37], v[56:57]
	v_lshlrev_b32_e32 v49, 16, v102
	v_add_f32_e32 v26, v26, v43
	v_add_f32_e32 v65, v26, v27
	v_mul_f32_e32 v26, 0xbfb8aa3b, v65
	v_exp_f32_e32 v26, v26
	v_and_b32_e32 v47, 0xffff0000, v102
	v_lshlrev_b32_e32 v45, 16, v103
	v_and_b32_e32 v43, 0xffff0000, v103
	global_load_dwordx4 v[100:103], v[40:41], off nt
	v_add_f32_e32 v28, 1.0, v26
	v_fma_f32 v29, v19, v64, v23
	v_pk_mul_f32 v[26:27], v[6:7], v[54:55]
	v_fma_f32 v63, v20, v63, v24
	v_add_f32_e32 v26, v26, v29
	v_add_f32_e32 v29, v26, v27
	v_mul_f32_e32 v26, 0xbfb8aa3b, v29
	v_exp_f32_e32 v64, v26
	v_pk_mul_f32 v[26:27], v[30:31], v[52:53]
	v_fma_f32 v62, v21, v62, v25
	v_add_f32_e32 v26, v26, v63
	v_add_f32_e32 v63, v26, v27
	v_mul_f32_e32 v26, 0xbfb8aa3b, v63
	v_exp_f32_e32 v26, v26
	v_add_f32_e32 v27, 1.0, v64
	v_rcp_f32_e32 v64, v27
	v_rcp_f32_e32 v28, v28
	v_add_f32_e32 v26, 1.0, v26
	v_rcp_f32_e32 v66, v26
	v_pk_mul_f32 v[26:27], v[8:9], v[50:51]
	v_mul_f32_e32 v29, v29, v64
	v_add_f32_e32 v26, v26, v62
	v_add_f32_e32 v62, v26, v27
	v_mul_f32_e32 v26, 0xbfb8aa3b, v62
	v_exp_f32_e32 v26, v26
	v_fma_f32 v61, v10, v61, v14
	v_mul_f32_e32 v28, v65, v28
	v_fma_f32 v60, v11, v60, v15
	v_add_f32_e32 v26, 1.0, v26
	v_rcp_f32_e32 v64, v26
	v_pk_mul_f32 v[26:27], v[32:33], v[48:49]
	v_fma_f32 v59, v12, v59, v16
	v_add_f32_e32 v26, v26, v61
	v_add_f32_e32 v61, v26, v27
	v_mul_f32_e32 v26, 0xbfb8aa3b, v61
	v_exp_f32_e32 v65, v26
	v_pk_mul_f32 v[26:27], v[2:3], v[46:47]
	v_mul_f32_e32 v62, v62, v64
	v_add_f32_e32 v26, v26, v60
	v_add_f32_e32 v60, v26, v27
	v_mul_f32_e32 v26, 0xbfb8aa3b, v60
	v_exp_f32_e32 v26, v26
	v_add_f32_e32 v27, 1.0, v65
	v_rcp_f32_e32 v64, v27
	v_mul_f32_e32 v63, v63, v66
	v_add_f32_e32 v65, 1.0, v26
	v_pk_mul_f32 v[26:27], v[34:35], v[44:45]
	v_fma_f32 v58, v13, v58, v17
	v_add_f32_e32 v26, v26, v59
	v_add_f32_e32 v59, v26, v27
	v_mul_f32_e32 v26, 0xbfb8aa3b, v59
	v_exp_f32_e32 v66, v26
	v_pk_mul_f32 v[26:27], v[4:5], v[42:43]
	v_mul_f32_e32 v61, v61, v64
	v_add_f32_e32 v26, v26, v58
	v_add_f32_e32 v26, v26, v27
	v_mul_f32_e32 v27, 0xbfb8aa3b, v26
	v_exp_f32_e32 v27, v27
	v_rcp_f32_e32 v58, v65
	v_add_f32_e32 v65, 1.0, v66
	v_rcp_f32_e32 v65, v65
	v_add_f32_e32 v27, 1.0, v27
	v_rcp_f32_e32 v27, v27
	v_mul_f32_e32 v58, v60, v58
	v_mul_f32_e32 v59, v59, v65
	v_lshl_add_u64 v[40:41], v[40:41], 0, s[8:9]
	v_mul_f32_e32 v60, v26, v27
	v_cvt_pk_bf16_f32 v26, v28, v29
	v_cvt_pk_bf16_f32 v27, v63, v62
	v_cvt_pk_bf16_f32 v28, v61, v58
	v_cvt_pk_bf16_f32 v29, v59, v60
	global_store_dwordx4 v[38:39], v[26:29], off
	v_lshl_add_u64 v[38:39], v[38:39], 0, s[8:9]
	v_mov_b32_e32 v65, v56
	v_mov_b32_e32 v64, v54
	v_mov_b32_e32 v63, v52
	v_mov_b32_e32 v62, v50
	v_mov_b32_e32 v61, v48
	v_mov_b32_e32 v60, v46
	v_mov_b32_e32 v59, v44
	v_mov_b32_e32 v58, v42
; __device__ __forceinline__ void unpack8(const u32x4 r, float (&o)[8]) { o[0] = bflo(r.x); o[1] = bfhi(r.x); o[2] = bflo(r.y); o[3] = bfhi(r.y); o[4] = bflo(r.z); o[5] = bfhi(r.z); o[6] = bflo(r.w); o[7] = bfhi(r.w); }
; __device__ __forceinline__ u32x4 pack8(const float (&o)[8]) { u32x4 r; r.x = pk2(o[0], o[1]); r.y = pk2(o[2], o[3]); r.z = pk2(o[4], o[5]); r.w = pk2(o[6], o[7]); return r; }
; __device__ __forceinline__ float siluf_(float x) { return x * __builtin_amdgcn_rcpf(1.0f + __expf(-x)); }
; __device__ __forceinline__ void phase_conv_pool(const Params& p, unsigned char* smem) {
;     ...
;             for (int t = t0; t < t1; ++t) {
;                 const u32x4 r2 = (((t + 1) & (SEQ - 1)) != 0) ? __builtin_nontemporal_load((const u32x4*)(src + 4096)) : zero;
;                 float x2[8], o[8]; unpack8(r2, x2);
; #pragma unroll
;                 for (int e = 0; e < 8; ++e) o[e] = siluf_(x0[e] * w0[e] + bb[e] + x1[e] * w1[e] + x2[e] * w2[e]);
;                 *(u32x4*)dst = pack8(o);
; #pragma unroll
;                 for (int e = 0; e < 8; ++e) { x0[e] = x1[e]; x1[e] = x2[e]; }
;                 src += 4096; dst += 4096;
;             }
.Lcv3_1:
	s_add_i32 s6, s6, 1
	s_and_b32 s7, s6, 0xfff
	v_mov_b32_e32 v42, v43
	v_mov_b32_e32 v44, v45
	v_mov_b32_e32 v46, v47
	v_mov_b32_e32 v48, v49
	v_mov_b32_e32 v50, v51
	v_mov_b32_e32 v52, v53
	v_mov_b32_e32 v54, v55
	v_mov_b32_e32 v56, v57
	s_cmp_eq_u32 s7, 0
	s_waitcnt vmcnt(8)
	s_cbranch_scc0 .Lcv3_go_1
	v_mov_b32_e32 v104, 0
	v_mov_b32_e32 v105, 0
	v_mov_b32_e32 v106, 0
	v_mov_b32_e32 v107, 0
.Lcv3_go_1:
	v_lshlrev_b32_e32 v57, 16, v104
	v_and_b32_e32 v55, 0xffff0000, v104
	v_lshlrev_b32_e32 v53, 16, v105
	v_and_b32_e32 v51, 0xffff0000, v105
	v_fma_f32 v43, v18, v65, v22
	v_pk_mul_f32 v[26:27], v[36:37], v[56:57]
	v_lshlrev_b32_e32 v49, 16, v106
	v_add_f32_e32 v26, v26, v43
	v_add_f32_e32 v65, v26, v27
	v_mul_f32_e32 v26, 0xbfb8aa3b, v65
	v_exp_f32_e32 v26, v26
	v_and_b32_e32 v47, 0xffff0000, v106
	v_lshlrev_b32_e32 v45, 16, v107
	v_and_b32_e32 v43, 0xffff0000, v107
	global_load_dwordx4 v[104:107], v[40:41], off nt
	v_add_f32_e32 v28, 1.0, v26
	v_fma_f32 v29, v19, v64, v23
	v_pk_mul_f32 v[26:27], v[6:7], v[54:55]
	v_fma_f32 v63, v20, v63, v24
	v_add_f32_e32 v26, v26, v29
	v_add_f32_e32 v29, v26, v27
	v_mul_f32_e32 v26, 0xbfb8aa3b, v29
	v_exp_f32_e32 v64, v26
	v_pk_mul_f32 v[26:27], v[30:31], v[52:53]
	v_fma_f32 v62, v21, v62, v25
	v_add_f32_e32 v26, v26, v63
	v_add_f32_e32 v63, v26, v27
	v_mul_f32_e32 v26, 0xbfb8aa3b, v63
	v_exp_f32_e32 v26, v26
	v_add_f32_e32 v27, 1.0, v64
	v_rcp_f32_e32 v64, v27
	v_rcp_f32_e32 v28, v28
	v_add_f32_e32 v26, 1.0, v26
	v_rcp_f32_e32 v66, v26
	v_pk_mul_f32 v[26:27], v[8:9], v[50:51]
	v_mul_f32_e32 v29, v29, v64
	v_add_f32_e32 v26, v26, v62
	v_add_f32_e32 v62, v26, v27
	v_mul_f32_e32 v26, 0xbfb8aa3b, v62
	v_exp_f32_e32 v26, v26
	v_fma_f32 v61, v10, v61, v14
	v_mul_f32_e32 v28, v65, v28
	v_fma_f32 v60, v11, v60, v15
	v_add_f32_e32 v26, 1.0, v26
	v_rcp_f32_e32 v64, v26
	v_pk_mul_f32 v[26:27], v[32:33], v[48:49]
	v_fma_f32 v59, v12, v59, v16
	v_add_f32_e32 v26, v26, v61
	v_add_f32_e32 v61, v26, v27
	v_mul_f32_e32 v26, 0xbfb8aa3b, v61
	v_exp_f32_e32 v65, v26
	v_pk_mul_f32 v[26:27], v[2:3], v[46:47]
	v_mul_f32_e32 v62, v62, v64
	v_add_f32_e32 v26, v26, v60
	v_add_f32_e32 v60, v26, v27
	v_mul_f32_e32 v26, 0xbfb8aa3b, v60
	v_exp_f32_e32 v26, v26
	v_add_f32_e32 v27, 1.0, v65
	v_rcp_f32_e32 v64, v27
	v_mul_f32_e32 v63, v63, v66
	v_add_f32_e32 v65, 1.0, v26
	v_pk_mul_f32 v[26:27], v[34:35], v[44:45]
	v_fma_f32 v58, v13, v58, v17
	v_add_f32_e32 v26, v26, v59
	v_add_f32_e32 v59, v26, v27
	v_mul_f32_e32 v26, 0xbfb8aa3b, v59
	v_exp_f32_e32 v66, v26
	v_pk_mul_f32 v[26:27], v[4:5], v[42:43]
	v_mul_f32_e32 v61, v61, v64
	v_add_f32_e32 v26, v26, v58
	v_add_f32_e32 v26, v26, v27
	v_mul_f32_e32 v27, 0xbfb8aa3b, v26
	v_exp_f32_e32 v27, v27
	v_rcp_f32_e32 v58, v65
	v_add_f32_e32 v65, 1.0, v66
	v_rcp_f32_e32 v65, v65
	v_add_f32_e32 v27, 1.0, v27
	v_rcp_f32_e32 v27, v27
	v_mul_f32_e32 v58, v60, v58
	v_mul_f32_e32 v59, v59, v65
	v_lshl_add_u64 v[40:41], v[40:41], 0, s[8:9]
	v_mul_f32_e32 v60, v26, v27
	v_cvt_pk_bf16_f32 v26, v28, v29
	v_cvt_pk_bf16_f32 v27, v63, v62
	v_cvt_pk_bf16_f32 v28, v61, v58
	v_cvt_pk_bf16_f32 v29, v59, v60
	global_store_dwordx4 v[38:39], v[26:29], off
	v_lshl_add_u64 v[38:39], v[38:39], 0, s[8:9]
	v_mov_b32_e32 v65, v56
	v_mov_b32_e32 v64, v54
	v_mov_b32_e32 v63, v52
	v_mov_b32_e32 v62, v50
	v_mov_b32_e32 v61, v48
	v_mov_b32_e32 v60, v46
	v_mov_b32_e32 v59, v44
	v_mov_b32_e32 v58, v42
.Lcv3_2:
	s_add_i32 s6, s6, 1
	s_and_b32 s7, s6, 0xfff
	v_mov_b32_e32 v42, v43
	v_mov_b32_e32 v44, v45
	v_mov_b32_e32 v46, v47
	v_mov_b32_e32 v48, v49
	v_mov_b32_e32 v50, v51
	v_mov_b32_e32 v52, v53
	v_mov_b32_e32 v54, v55
	v_mov_b32_e32 v56, v57
	s_cmp_eq_u32 s7, 0
	s_waitcnt vmcnt(9)
	s_cbranch_scc0 .Lcv3_go_2
	v_mov_b32_e32 v108, 0
	v_mov_b32_e32 v109, 0
	v_mov_b32_e32 v110, 0
	v_mov_b32_e32 v111, 0
.Lcv3_go_2:
	v_lshlrev_b32_e32 v57, 16, v108
	v_and_b32_e32 v55, 0xffff0000, v108
	v_lshlrev_b32_e32 v53, 16, v109
	v_and_b32_e32 v51, 0xffff0000, v109
	v_fma_f32 v43, v18, v65, v22
	v_pk_mul_f32 v[26:27], v[36:37], v[56:57]
	v_lshlrev_b32_e32 v49, 16, v110
	v_add_f32_e32 v26, v26, v43
	v_add_f32_e32 v65, v26, v27
	v_mul_f32_e32 v26, 0xbfb8aa3b, v65
	v_exp_f32_e32 v26, v26
	v_and_b32_e32 v47, 0xffff0000, v110
	v_lshlrev_b32_e32 v45, 16, v111
	v_and_b32_e32 v43, 0xffff0000, v111
	global_load_dwordx4 v[108:111], v[40:41], off nt
	v_add_f32_e32 v28, 1.0, v26
	v_fma_f32 v29, v19, v64, v23
	v_pk_mul_f32 v[26:27], v[6:7], v[54:55]
	v_fma_f32 v63, v20, v63, v24
	v_add_f32_e32 v26, v26, v29
	v_add_f32_e32 v29, v26, v27
	v_mul_f32_e32 v26, 0xbfb8aa3b, v29
	v_exp_f32_e32 v64, v26
	v_pk_mul_f32 v[26:27], v[30:31], v[52:53]
	v_fma_f32 v62, v21, v62, v25
	v_add_f32_e32 v26, v26, v63
	v_add_f32_e32 v63, v26, v27
	v_mul_f32_e32 v26, 0xbfb8aa3b, v63
	v_exp_f32_e32 v26, v26
	v_add_f32_e32 v27, 1.0, v64
	v_rcp_f32_e32 v64, v27
	v_rcp_f32_e32 v28, v28
	v_add_f32_e32 v26, 1.0, v26
	v_rcp_f32_e32 v66, v26
	v_pk_mul_f32 v[26:27], v[8:9], v[50:51]
	v_mul_f32_e32 v29, v29, v64
	v_add_f32_e32 v26, v26, v62
	v_add_f32_e32 v62, v26, v27
	v_mul_f32_e32 v26, 0xbfb8aa3b, v62
	v_exp_f32_e32 v26, v26
	v_fma_f32 v61, v10, v61, v14
	v_mul_f32_e32 v28, v65, v28
	v_fma_f32 v60, v11, v60, v15
	v_add_f32_e32 v26, 1.0, v26
	v_rcp_f32_e32 v64, v26
	v_pk_mul_f32 v[26:27], v[32:33], v[48:49]
	v_fma_f32 v59, v12, v59, v16
	v_add_f32_e32 v26, v26, v61
	v_add_f32_e32 v61, v26, v27
	v_mul_f32_e32 v26, 0xbfb8aa3b, v61
	v_exp_f32_e32 v65, v26
	v_pk_mul_f32 v[26:27], v[2:3], v[46:47]
	v_mul_f32_e32 v62, v62, v64
	v_add_f32_e32 v26, v26, v60
	v_add_f32_e32 v60, v26, v27
	v_mul_f32_e32 v26, 0xbfb8aa3b, v60
	v_exp_f32_e32 v26, v26
	v_add_f32_e32 v27, 1.0, v65
	v_rcp_f32_e32 v64, v27
	v_mul_f32_e32 v63, v63, v66
	v_add_f32_e32 v65, 1.0, v26
	v_pk_mul_f32 v[26:27], v[34:35], v[44:45]
	v_fma_f32 v58, v13, v58, v17
	v_add_f32_e32 v26, v26, v59
	v_add_f32_e32 v59, v26, v27
	v_mul_f32_e32 v26, 0xbfb8aa3b, v59
	v_exp_f32_e32 v66, v26
	v_pk_mul_f32 v[26:27], v[4:5], v[42:43]
	v_mul_f32_e32 v61, v61, v64
	v_add_f32_e32 v26, v26, v58
	v_add_f32_e32 v26, v26, v27
	v_mul_f32_e32 v27, 0xbfb8aa3b, v26
	v_exp_f32_e32 v27, v27
	v_rcp_f32_e32 v58, v65
	v_add_f32_e32 v65, 1.0, v66
	v_rcp_f32_e32 v65, v65
	v_add_f32_e32 v27, 1.0, v27
	v_rcp_f32_e32 v27, v27
	v_mul_f32_e32 v58, v60, v58
	v_mul_f32_e32 v59, v59, v65
	v_lshl_add_u64 v[40:41], v[40:41], 0, s[8:9]
	v_mul_f32_e32 v60, v26, v27
	v_cvt_pk_bf16_f32 v26, v28, v29
	v_cvt_pk_bf16_f32 v27, v63, v62
	v_cvt_pk_bf16_f32 v28, v61, v58
	v_cvt_pk_bf16_f32 v29, v59, v60
	global_store_dwordx4 v[38:39], v[26:29], off
	v_lshl_add_u64 v[38:39], v[38:39], 0, s[8:9]
	v_mov_b32_e32 v65, v56
	v_mov_b32_e32 v64, v54
	v_mov_b32_e32 v63, v52
	v_mov_b32_e32 v62, v50
	v_mov_b32_e32 v61, v48
	v_mov_b32_e32 v60, v46
	v_mov_b32_e32 v59, v44
	v_mov_b32_e32 v58, v42
; __device__ __forceinline__ void unpack8(const u32x4 r, float (&o)[8]) { o[0] = bflo(r.x); o[1] = bfhi(r.x); o[2] = bflo(r.y); o[3] = bfhi(r.y); o[4] = bflo(r.z); o[5] = bfhi(r.z); o[6] = bflo(r.w); o[7] = bfhi(r.w); }
; __device__ __forceinline__ u32x4 pack8(const float (&o)[8]) { u32x4 r; r.x = pk2(o[0], o[1]); r.y = pk2(o[2], o[3]); r.z = pk2(o[4], o[5]); r.w = pk2(o[6], o[7]); return r; }
; __device__ __forceinline__ float siluf_(float x) { return x * __builtin_amdgcn_rcpf(1.0f + __expf(-x)); }
; __device__ __forceinline__ void phase_conv_pool(const Params& p, unsigned char* smem) {
;     ...
;             for (int t = t0; t < t1; ++t) {
;                 const u32x4 r2 = (((t + 1) & (SEQ - 1)) != 0) ? __builtin_nontemporal_load((const u32x4*)(src + 4096)) : zero;
;                 float x2[8], o[8]; unpack8(r2, x2);
; #pragma unroll
;                 for (int e = 0; e < 8; ++e) o[e] = siluf_(x0[e] * w0[e] + bb[e] + x1[e] * w1[e] + x2[e] * w2[e]);
;                 *(u32x4*)dst = pack8(o);
; #pragma unroll
;                 for (int e = 0; e < 8; ++e) { x0[e] = x1[e]; x1[e] = x2[e]; }
;                 src += 4096; dst += 4096;
;             }
.Lcv3_3:
	s_add_i32 s6, s6, 1
	s_and_b32 s7, s6, 0xfff
	v_mov_b32_e32 v42, v43
	v_mov_b32_e32 v44, v45
	v_mov_b32_e32 v46, v47
	v_mov_b32_e32 v48, v49
	v_mov_b32_e32 v50, v51
	v_mov_b32_e32 v52, v53
	v_mov_b32_e32 v54, v55
	v_mov_b32_e32 v56, v57
	s_cmp_eq_u32 s7, 0
	s_waitcnt vmcnt(10)
	s_cbranch_scc0 .Lcv3_go_3
	v_mov_b32_e32 v112, 0
	v_mov_b32_e32 v113, 0
	v_mov_b32_e32 v114, 0
	v_mov_b32_e32 v115, 0
.Lcv3_go_3:
	v_lshlrev_b32_e32 v57, 16, v112
	v_and_b32_e32 v55, 0xffff0000, v112
	v_lshlrev_b32_e32 v53, 16, v113
	v_and_b32_e32 v51, 0xffff0000, v113
	v_fma_f32 v43, v18, v65, v22
	v_pk_mul_f32 v[26:27], v[36:37], v[56:57]
	v_lshlrev_b32_e32 v49, 16, v114
	v_add_f32_e32 v26, v26, v43
	v_add_f32_e32 v65, v26, v27
	v_mul_f32_e32 v26, 0xbfb8aa3b, v65
	v_exp_f32_e32 v26, v26
	v_and_b32_e32 v47, 0xffff0000, v114
	v_lshlrev_b32_e32 v45, 16, v115
	v_and_b32_e32 v43, 0xffff0000, v115
	global_load_dwordx4 v[112:115], v[40:41], off nt
	v_add_f32_e32 v28, 1.0, v26
	v_fma_f32 v29, v19, v64, v23
	v_pk_mul_f32 v[26:27], v[6:7], v[54:55]
	v_fma_f32 v63, v20, v63, v24
	v_add_f32_e32 v26, v26, v29
	v_add_f32_e32 v29, v26, v27
	v_mul_f32_e32 v26, 0xbfb8aa3b, v29
	v_exp_f32_e32 v64, v26
	v_pk_mul_f32 v[26:27], v[30:31], v[52:53]
	v_fma_f32 v62, v21, v62, v25
	v_add_f32_e32 v26, v26, v63
	v_add_f32_e32 v63, v26, v27
	v_mul_f32_e32 v26, 0xbfb8aa3b, v63
	v_exp_f32_e32 v26, v26
	v_add_f32_e32 v27, 1.0, v64
	v_rcp_f32_e32 v64, v27
	v_rcp_f32_e32 v28, v28
	v_add_f32_e32 v26, 1.0, v26
	v_rcp_f32_e32 v66, v26
	v_pk_mul_f32 v[26:27], v[8:9], v[50:51]
	v_mul_f32_e32 v29, v29, v64
	v_add_f32_e32 v26, v26, v62
	v_add_f32_e32 v62, v26, v27
	v_mul_f32_e32 v26, 0xbfb8aa3b, v62
	v_exp_f32_e32 v26, v26
	v_fma_f32 v61, v10, v61, v14
	v_mul_f32_e32 v28, v65, v28
	v_fma_f32 v60, v11, v60, v15
	v_add_f32_e32 v26, 1.0, v26
	v_rcp_f32_e32 v64, v26
	v_pk_mul_f32 v[26:27], v[32:33], v[48:49]
	v_fma_f32 v59, v12, v59, v16
	v_add_f32_e32 v26, v26, v61
	v_add_f32_e32 v61, v26, v27
	v_mul_f32_e32 v26, 0xbfb8aa3b, v61
	v_exp_f32_e32 v65, v26
	v_pk_mul_f32 v[26:27], v[2:3], v[46:47]
	v_mul_f32_e32 v62, v62, v64
	v_add_f32_e32 v26, v26, v60
	v_add_f32_e32 v60, v26, v27
	v_mul_f32_e32 v26, 0xbfb8aa3b, v60
	v_exp_f32_e32 v26, v26
	v_add_f32_e32 v27, 1.0, v65
	v_rcp_f32_e32 v64, v27
	v_mul_f32_e32 v63, v63, v66
	v_add_f32_e32 v65, 1.0, v26
	v_pk_mul_f32 v[26:27], v[34:35], v[44:45]
	v_fma_f32 v58, v13, v58, v17
	v_add_f32_e32 v26, v26, v59
	v_add_f32_e32 v59, v26, v27
	v_mul_f32_e32 v26, 0xbfb8aa3b, v59
	v_exp_f32_e32 v66, v26
	v_pk_mul_f32 v[26:27], v[4:5], v[42:43]
	v_mul_f32_e32 v61, v61, v64
	v_add_f32_e32 v26, v26, v58
	v_add_f32_e32 v26, v26, v27
	v_mul_f32_e32 v27, 0xbfb8aa3b, v26
	v_exp_f32_e32 v27, v27
	v_rcp_f32_e32 v58, v65
	v_add_f32_e32 v65, 1.0, v66
	v_rcp_f32_e32 v65, v65
	v_add_f32_e32 v27, 1.0, v27
	v_rcp_f32_e32 v27, v27
	v_mul_f32_e32 v58, v60, v58
	v_mul_f32_e32 v59, v59, v65
	v_lshl_add_u64 v[40:41], v[40:41], 0, s[8:9]
	v_mul_f32_e32 v60, v26, v27
	v_cvt_pk_bf16_f32 v26, v28, v29
	v_cvt_pk_bf16_f32 v27, v63, v62
	v_cvt_pk_bf16_f32 v28, v61, v58
	v_cvt_pk_bf16_f32 v29, v59, v60
	global_store_dwordx4 v[38:39], v[26:29], off
	v_lshl_add_u64 v[38:39], v[38:39], 0, s[8:9]
	v_mov_b32_e32 v65, v56
	v_mov_b32_e32 v64, v54
	v_mov_b32_e32 v63, v52
	v_mov_b32_e32 v62, v50
	v_mov_b32_e32 v61, v48
	v_mov_b32_e32 v60, v46
	v_mov_b32_e32 v59, v44
	v_mov_b32_e32 v58, v42
.Lcv3_4:
	s_add_i32 s6, s6, 1
	s_and_b32 s7, s6, 0xfff
	v_mov_b32_e32 v42, v43
	v_mov_b32_e32 v44, v45
	v_mov_b32_e32 v46, v47
	v_mov_b32_e32 v48, v49
	v_mov_b32_e32 v50, v51
	v_mov_b32_e32 v52, v53
	v_mov_b32_e32 v54, v55
	v_mov_b32_e32 v56, v57
	s_cmp_eq_u32 s7, 0
	s_waitcnt vmcnt(11)
	s_cbranch_scc0 .Lcv3_go_4
	v_mov_b32_e32 v116, 0
	v_mov_b32_e32 v117, 0
	v_mov_b32_e32 v118, 0
	v_mov_b32_e32 v119, 0
.Lcv3_go_4:
	v_lshlrev_b32_e32 v57, 16, v116
	v_and_b32_e32 v55, 0xffff0000, v116
	v_lshlrev_b32_e32 v53, 16, v117
	v_and_b32_e32 v51, 0xffff0000, v117
	v_fma_f32 v43, v18, v65, v22
	v_pk_mul_f32 v[26:27], v[36:37], v[56:57]
	v_lshlrev_b32_e32 v49, 16, v118
	v_add_f32_e32 v26, v26, v43
	v_add_f32_e32 v65, v26, v27
	v_mul_f32_e32 v26, 0xbfb8aa3b, v65
	v_exp_f32_e32 v26, v26
	v_and_b32_e32 v47, 0xffff0000, v118
	v_lshlrev_b32_e32 v45, 16, v119
	v_and_b32_e32 v43, 0xffff0000, v119
	global_load_dwordx4 v[116:119], v[40:41], off nt
	v_add_f32_e32 v28, 1.0, v26
	v_fma_f32 v29, v19, v64, v23
	v_pk_mul_f32 v[26:27], v[6:7], v[54:55]
	v_fma_f32 v63, v20, v63, v24
	v_add_f32_e32 v26, v26, v29
	v_add_f32_e32 v29, v26, v27
	v_mul_f32_e32 v26, 0xbfb8aa3b, v29
	v_exp_f32_e32 v64, v26
	v_pk_mul_f32 v[26:27], v[30:31], v[52:53]
	v_fma_f32 v62, v21, v62, v25
	v_add_f32_e32 v26, v26, v63
	v_add_f32_e32 v63, v26, v27
	v_mul_f32_e32 v26, 0xbfb8aa3b, v63
	v_exp_f32_e32 v26, v26
	v_add_f32_e32 v27, 1.0, v64
	v_rcp_f32_e32 v64, v27
	v_rcp_f32_e32 v28, v28
	v_add_f32_e32 v26, 1.0, v26
	v_rcp_f32_e32 v66, v26
	v_pk_mul_f32 v[26:27], v[8:9], v[50:51]
	v_mul_f32_e32 v29, v29, v64
	v_add_f32_e32 v26, v26, v62
	v_add_f32_e32 v62, v26, v27
	v_mul_f32_e32 v26, 0xbfb8aa3b, v62
	v_exp_f32_e32 v26, v26
	v_fma_f32 v61, v10, v61, v14
	v_mul_f32_e32 v28, v65, v28
	v_fma_f32 v60, v11, v60, v15
	v_add_f32_e32 v26, 1.0, v26
	v_rcp_f32_e32 v64, v26
	v_pk_mul_f32 v[26:27], v[32:33], v[48:49]
	v_fma_f32 v59, v12, v59, v16
	v_add_f32_e32 v26, v26, v61
	v_add_f32_e32 v61, v26, v27
	v_mul_f32_e32 v26, 0xbfb8aa3b, v61
	v_exp_f32_e32 v65, v26
	v_pk_mul_f32 v[26:27], v[2:3], v[46:47]
	v_mul_f32_e32 v62, v62, v64
	v_add_f32_e32 v26, v26, v60
	v_add_f32_e32 v60, v26, v27
	v_mul_f32_e32 v26, 0xbfb8aa3b, v60
	v_exp_f32_e32 v26, v26
	v_add_f32_e32 v27, 1.0, v65
	v_rcp_f32_e32 v64, v27
	v_mul_f32_e32 v63, v63, v66
	v_add_f32_e32 v65, 1.0, v26
	v_pk_mul_f32 v[26:27], v[34:35], v[44:45]
	v_fma_f32 v58, v13, v58, v17
	v_add_f32_e32 v26, v26, v59
	v_add_f32_e32 v59, v26, v27
	v_mul_f32_e32 v26, 0xbfb8aa3b, v59
	v_exp_f32_e32 v66, v26
	v_pk_mul_f32 v[26:27], v[4:5], v[42:43]
	v_mul_f32_e32 v61, v61, v64
	v_add_f32_e32 v26, v26, v58
	v_add_f32_e32 v26, v26, v27
	v_mul_f32_e32 v27, 0xbfb8aa3b, v26
	v_exp_f32_e32 v27, v27
	v_rcp_f32_e32 v58, v65
	v_add_f32_e32 v65, 1.0, v66
	v_rcp_f32_e32 v65, v65
	v_add_f32_e32 v27, 1.0, v27
	v_rcp_f32_e32 v27, v27
	v_mul_f32_e32 v58, v60, v58
	v_mul_f32_e32 v59, v59, v65
	v_lshl_add_u64 v[40:41], v[40:41], 0, s[8:9]
	v_mul_f32_e32 v60, v26, v27
	v_cvt_pk_bf16_f32 v26, v28, v29
	v_cvt_pk_bf16_f32 v27, v63, v62
	v_cvt_pk_bf16_f32 v28, v61, v58
	v_cvt_pk_bf16_f32 v29, v59, v60
	global_store_dwordx4 v[38:39], v[26:29], off
	v_lshl_add_u64 v[38:39], v[38:39], 0, s[8:9]
	v_mov_b32_e32 v65, v56
	v_mov_b32_e32 v64, v54
	v_mov_b32_e32 v63, v52
	v_mov_b32_e32 v62, v50
	v_mov_b32_e32 v61, v48
	v_mov_b32_e32 v60, v46
	v_mov_b32_e32 v59, v44
	v_mov_b32_e32 v58, v42
; __device__ __forceinline__ void unpack8(const u32x4 r, float (&o)[8]) { o[0] = bflo(r.x); o[1] = bfhi(r.x); o[2] = bflo(r.y); o[3] = bfhi(r.y); o[4] = bflo(r.z); o[5] = bfhi(r.z); o[6] = bflo(r.w); o[7] = bfhi(r.w); }
; __device__ __forceinline__ u32x4 pack8(const float (&o)[8]) { u32x4 r; r.x = pk2(o[0], o[1]); r.y = pk2(o[2], o[3]); r.z = pk2(o[4], o[5]); r.w = pk2(o[6], o[7]); return r; }
; __device__ __forceinline__ float siluf_(float x) { return x * __builtin_amdgcn_rcpf(1.0f + __expf(-x)); }
; __device__ __forceinline__ void phase_conv_pool(const Params& p, unsigned char* smem) {
;     ...
;             for (int t = t0; t < t1; ++t) {
;                 const u32x4 r2 = (((t + 1) & (SEQ - 1)) != 0) ? __builtin_nontemporal_load((const u32x4*)(src + 4096)) : zero;
;                 float x2[8], o[8]; unpack8(r2, x2);
; #pragma unroll
;                 for (int e = 0; e < 8; ++e) o[e] = siluf_(x0[e] * w0[e] + bb[e] + x1[e] * w1[e] + x2[e] * w2[e]);
;                 *(u32x4*)dst = pack8(o);
; #pragma unroll
;                 for (int e = 0; e < 8; ++e) { x0[e] = x1[e]; x1[e] = x2[e]; }
;                 src += 4096; dst += 4096;
;             }
.Lcv3_5:
	s_add_i32 s6, s6, 1
	s_and_b32 s7, s6, 0xfff
	v_mov_b32_e32 v42, v43
	v_mov_b32_e32 v44, v45
	v_mov_b32_e32 v46, v47
	v_mov_b32_e32 v48, v49
	v_mov_b32_e32 v50, v51
	v_mov_b32_e32 v52, v53
	v_mov_b32_e32 v54, v55
	v_mov_b32_e32 v56, v57
	s_cmp_eq_u32 s7, 0
	s_waitcnt vmcnt(12)
	s_cbranch_scc0 .Lcv3_go_5
	v_mov_b32_e32 v120, 0
	v_mov_b32_e32 v121, 0
	v_mov_b32_e32 v122, 0
	v_mov_b32_e32 v123, 0
.Lcv3_go_5:
	v_lshlrev_b32_e32 v57, 16, v120
	v_and_b32_e32 v55, 0xffff0000, v120
	v_lshlrev_b32_e32 v53, 16, v121
	v_and_b32_e32 v51, 0xffff0000, v121
	v_fma_f32 v43, v18, v65, v22
	v_pk_mul_f32 v[26:27], v[36:37], v[56:57]
	v_lshlrev_b32_e32 v49, 16, v122
	v_add_f32_e32 v26, v26, v43
	v_add_f32_e32 v65, v26, v27
	v_mul_f32_e32 v26, 0xbfb8aa3b, v65
	v_exp_f32_e32 v26, v26
	v_and_b32_e32 v47, 0xffff0000, v122
	v_lshlrev_b32_e32 v45, 16, v123
	v_and_b32_e32 v43, 0xffff0000, v123
	global_load_dwordx4 v[120:123], v[40:41], off nt
	v_add_f32_e32 v28, 1.0, v26
	v_fma_f32 v29, v19, v64, v23
	v_pk_mul_f32 v[26:27], v[6:7], v[54:55]
	v_fma_f32 v63, v20, v63, v24
	v_add_f32_e32 v26, v26, v29
	v_add_f32_e32 v29, v26, v27
	v_mul_f32_e32 v26, 0xbfb8aa3b, v29
	v_exp_f32_e32 v64, v26
	v_pk_mul_f32 v[26:27], v[30:31], v[52:53]
	v_fma_f32 v62, v21, v62, v25
	v_add_f32_e32 v26, v26, v63
	v_add_f32_e32 v63, v26, v27
	v_mul_f32_e32 v26, 0xbfb8aa3b, v63
	v_exp_f32_e32 v26, v26
	v_add_f32_e32 v27, 1.0, v64
	v_rcp_f32_e32 v64, v27
	v_rcp_f32_e32 v28, v28
	v_add_f32_e32 v26, 1.0, v26
	v_rcp_f32_e32 v66, v26
	v_pk_mul_f32 v[26:27], v[8:9], v[50:51]
	v_mul_f32_e32 v29, v29, v64
	v_add_f32_e32 v26, v26, v62
	v_add_f32_e32 v62, v26, v27
	v_mul_f32_e32 v26, 0xbfb8aa3b, v62
	v_exp_f32_e32 v26, v26
	v_fma_f32 v61, v10, v61, v14
	v_mul_f32_e32 v28, v65, v28
	v_fma_f32 v60, v11, v60, v15
	v_add_f32_e32 v26, 1.0, v26
	v_rcp_f32_e32 v64, v26
	v_pk_mul_f32 v[26:27], v[32:33], v[48:49]
	v_fma_f32 v59, v12, v59, v16
	v_add_f32_e32 v26, v26, v61
	v_add_f32_e32 v61, v26, v27
	v_mul_f32_e32 v26, 0xbfb8aa3b, v61
	v_exp_f32_e32 v65, v26
	v_pk_mul_f32 v[26:27], v[2:3], v[46:47]
	v_mul_f32_e32 v62, v62, v64
	v_add_f32_e32 v26, v26, v60
	v_add_f32_e32 v60, v26, v27
	v_mul_f32_e32 v26, 0xbfb8aa3b, v60
	v_exp_f32_e32 v26, v26
	v_add_f32_e32 v27, 1.0, v65
	v_rcp_f32_e32 v64, v27
	v_mul_f32_e32 v63, v63, v66
	v_add_f32_e32 v65, 1.0, v26
	v_pk_mul_f32 v[26:27], v[34:35], v[44:45]
	v_fma_f32 v58, v13, v58, v17
	v_add_f32_e32 v26, v26, v59
	v_add_f32_e32 v59, v26, v27
	v_mul_f32_e32 v26, 0xbfb8aa3b, v59
	v_exp_f32_e32 v66, v26
	v_pk_mul_f32 v[26:27], v[4:5], v[42:43]
	v_mul_f32_e32 v61, v61, v64
	v_add_f32_e32 v26, v26, v58
	v_add_f32_e32 v26, v26, v27
	v_mul_f32_e32 v27, 0xbfb8aa3b, v26
	v_exp_f32_e32 v27, v27
	v_rcp_f32_e32 v58, v65
	v_add_f32_e32 v65, 1.0, v66
	v_rcp_f32_e32 v65, v65
	v_add_f32_e32 v27, 1.0, v27
	v_rcp_f32_e32 v27, v27
	v_mul_f32_e32 v58, v60, v58
	v_mul_f32_e32 v59, v59, v65
	v_lshl_add_u64 v[40:41], v[40:41], 0, s[8:9]
	v_mul_f32_e32 v60, v26, v27
	v_cvt_pk_bf16_f32 v26, v28, v29
	v_cvt_pk_bf16_f32 v27, v63, v62
	v_cvt_pk_bf16_f32 v28, v61, v58
	v_cvt_pk_bf16_f32 v29, v59, v60
	global_store_dwordx4 v[38:39], v[26:29], off
	v_lshl_add_u64 v[38:39], v[38:39], 0, s[8:9]
	v_mov_b32_e32 v65, v56
	v_mov_b32_e32 v64, v54
	v_mov_b32_e32 v63, v52
	v_mov_b32_e32 v62, v50
	v_mov_b32_e32 v61, v48
	v_mov_b32_e32 v60, v46
	v_mov_b32_e32 v59, v44
	v_mov_b32_e32 v58, v42
.Lcv3_6:
	s_add_i32 s6, s6, 1
	s_and_b32 s7, s6, 0xfff
	v_mov_b32_e32 v42, v43
	v_mov_b32_e32 v44, v45
	v_mov_b32_e32 v46, v47
	v_mov_b32_e32 v48, v49
	v_mov_b32_e32 v50, v51
	v_mov_b32_e32 v52, v53
	v_mov_b32_e32 v54, v55
	v_mov_b32_e32 v56, v57
	s_cmp_eq_u32 s7, 0
	s_waitcnt vmcnt(13)
	s_cbranch_scc0 .Lcv3_go_6
	v_mov_b32_e32 v124, 0
	v_mov_b32_e32 v125, 0
	v_mov_b32_e32 v126, 0
	v_mov_b32_e32 v127, 0
; __device__ __forceinline__ void unpack8(const u32x4 r, float (&o)[8]) { o[0] = bflo(r.x); o[1] = bfhi(r.x); o[2] = bflo(r.y); o[3] = bfhi(r.y); o[4] = bflo(r.z); o[5] = bfhi(r.z); o[6] = bflo(r.w); o[7] = bfhi(r.w); }
; __device__ __forceinline__ u32x4 pack8(const float (&o)[8]) { u32x4 r; r.x = pk2(o[0], o[1]); r.y = pk2(o[2], o[3]); r.z = pk2(o[4], o[5]); r.w = pk2(o[6], o[7]); return r; }
; __device__ __forceinline__ float siluf_(float x) { return x * __builtin_amdgcn_rcpf(1.0f + __expf(-x)); }
; __device__ __forceinline__ void phase_conv_pool(const Params& p, unsigned char* smem) {
;     ...
;             for (int t = t0; t < t1; ++t) {
;                 const u32x4 r2 = (((t + 1) & (SEQ - 1)) != 0) ? __builtin_nontemporal_load((const u32x4*)(src + 4096)) : zero;
;                 float x2[8], o[8]; unpack8(r2, x2);
; #pragma unroll
;                 for (int e = 0; e < 8; ++e) o[e] = siluf_(x0[e] * w0[e] + bb[e] + x1[e] * w1[e] + x2[e] * w2[e]);
;                 *(u32x4*)dst = pack8(o);
; #pragma unroll
;                 for (int e = 0; e < 8; ++e) { x0[e] = x1[e]; x1[e] = x2[e]; }
;                 src += 4096; dst += 4096;
;             }
.Lcv3_go_6:
	v_lshlrev_b32_e32 v57, 16, v124
	v_and_b32_e32 v55, 0xffff0000, v124
	v_lshlrev_b32_e32 v53, 16, v125
	v_and_b32_e32 v51, 0xffff0000, v125
	v_fma_f32 v43, v18, v65, v22
	v_pk_mul_f32 v[26:27], v[36:37], v[56:57]
	v_lshlrev_b32_e32 v49, 16, v126
	v_add_f32_e32 v26, v26, v43
	v_add_f32_e32 v65, v26, v27
	v_mul_f32_e32 v26, 0xbfb8aa3b, v65
	v_exp_f32_e32 v26, v26
	v_and_b32_e32 v47, 0xffff0000, v126
	v_lshlrev_b32_e32 v45, 16, v127
	v_and_b32_e32 v43, 0xffff0000, v127
	global_load_dwordx4 v[124:127], v[40:41], off nt
	v_add_f32_e32 v28, 1.0, v26
	v_fma_f32 v29, v19, v64, v23
	v_pk_mul_f32 v[26:27], v[6:7], v[54:55]
	v_fma_f32 v63, v20, v63, v24
	v_add_f32_e32 v26, v26, v29
	v_add_f32_e32 v29, v26, v27
	v_mul_f32_e32 v26, 0xbfb8aa3b, v29
	v_exp_f32_e32 v64, v26
	v_pk_mul_f32 v[26:27], v[30:31], v[52:53]
	v_fma_f32 v62, v21, v62, v25
	v_add_f32_e32 v26, v26, v63
	v_add_f32_e32 v63, v26, v27
	v_mul_f32_e32 v26, 0xbfb8aa3b, v63
	v_exp_f32_e32 v26, v26
	v_add_f32_e32 v27, 1.0, v64
	v_rcp_f32_e32 v64, v27
	v_rcp_f32_e32 v28, v28
	v_add_f32_e32 v26, 1.0, v26
	v_rcp_f32_e32 v66, v26
	v_pk_mul_f32 v[26:27], v[8:9], v[50:51]
	v_mul_f32_e32 v29, v29, v64
	v_add_f32_e32 v26, v26, v62
	v_add_f32_e32 v62, v26, v27
	v_mul_f32_e32 v26, 0xbfb8aa3b, v62
	v_exp_f32_e32 v26, v26
	v_fma_f32 v61, v10, v61, v14
	v_mul_f32_e32 v28, v65, v28
	v_fma_f32 v60, v11, v60, v15
	v_add_f32_e32 v26, 1.0, v26
	v_rcp_f32_e32 v64, v26
	v_pk_mul_f32 v[26:27], v[32:33], v[48:49]
	v_fma_f32 v59, v12, v59, v16
	v_add_f32_e32 v26, v26, v61
	v_add_f32_e32 v61, v26, v27
	v_mul_f32_e32 v26, 0xbfb8aa3b, v61
	v_exp_f32_e32 v65, v26
	v_pk_mul_f32 v[26:27], v[2:3], v[46:47]
	v_mul_f32_e32 v62, v62, v64
	v_add_f32_e32 v26, v26, v60
	v_add_f32_e32 v60, v26, v27
	v_mul_f32_e32 v26, 0xbfb8aa3b, v60
	v_exp_f32_e32 v26, v26
	v_add_f32_e32 v27, 1.0, v65
	v_rcp_f32_e32 v64, v27
	v_mul_f32_e32 v63, v63, v66
	v_add_f32_e32 v65, 1.0, v26
	v_pk_mul_f32 v[26:27], v[34:35], v[44:45]
	v_fma_f32 v58, v13, v58, v17
	v_add_f32_e32 v26, v26, v59
	v_add_f32_e32 v59, v26, v27
	v_mul_f32_e32 v26, 0xbfb8aa3b, v59
	v_exp_f32_e32 v66, v26
	v_pk_mul_f32 v[26:27], v[4:5], v[42:43]
	v_mul_f32_e32 v61, v61, v64
	v_add_f32_e32 v26, v26, v58
	v_add_f32_e32 v26, v26, v27
	v_mul_f32_e32 v27, 0xbfb8aa3b, v26
	v_exp_f32_e32 v27, v27
	v_rcp_f32_e32 v58, v65
	v_add_f32_e32 v65, 1.0, v66
	v_rcp_f32_e32 v65, v65
	v_add_f32_e32 v27, 1.0, v27
	v_rcp_f32_e32 v27, v27
	v_mul_f32_e32 v58, v60, v58
	v_mul_f32_e32 v59, v59, v65
	v_lshl_add_u64 v[40:41], v[40:41], 0, s[8:9]
	v_mul_f32_e32 v60, v26, v27
	v_cvt_pk_bf16_f32 v26, v28, v29
	v_cvt_pk_bf16_f32 v27, v63, v62
	v_cvt_pk_bf16_f32 v28, v61, v58
	v_cvt_pk_bf16_f32 v29, v59, v60
	global_store_dwordx4 v[38:39], v[26:29], off
	v_lshl_add_u64 v[38:39], v[38:39], 0, s[8:9]
	v_mov_b32_e32 v65, v56
	v_mov_b32_e32 v64, v54
	v_mov_b32_e32 v63, v52
	v_mov_b32_e32 v62, v50
	v_mov_b32_e32 v61, v48
	v_mov_b32_e32 v60, v46
	v_mov_b32_e32 v59, v44
	v_mov_b32_e32 v58, v42
.Lcv3_7:
	s_add_i32 s6, s6, 1
	s_and_b32 s7, s6, 0xfff
	v_mov_b32_e32 v42, v43
	v_mov_b32_e32 v44, v45
	v_mov_b32_e32 v46, v47
	v_mov_b32_e32 v48, v49
	v_mov_b32_e32 v50, v51
	v_mov_b32_e32 v52, v53
	v_mov_b32_e32 v54, v55
	v_mov_b32_e32 v56, v57
	s_cmp_eq_u32 s7, 0
	s_waitcnt vmcnt(14)
	s_cbranch_scc0 .Lcv3_go_7
	v_mov_b32_e32 v128, 0
	v_mov_b32_e32 v129, 0
	v_mov_b32_e32 v130, 0
	v_mov_b32_e32 v131, 0
.Lcv3_go_7:
	v_lshlrev_b32_e32 v57, 16, v128
	v_and_b32_e32 v55, 0xffff0000, v128
	v_lshlrev_b32_e32 v53, 16, v129
	v_and_b32_e32 v51, 0xffff0000, v129
	v_fma_f32 v43, v18, v65, v22
	v_pk_mul_f32 v[26:27], v[36:37], v[56:57]
	v_lshlrev_b32_e32 v49, 16, v130
	v_add_f32_e32 v26, v26, v43
	v_add_f32_e32 v65, v26, v27
	v_mul_f32_e32 v26, 0xbfb8aa3b, v65
	v_exp_f32_e32 v26, v26
	v_and_b32_e32 v47, 0xffff0000, v130
	v_lshlrev_b32_e32 v45, 16, v131
	v_and_b32_e32 v43, 0xffff0000, v131
	global_load_dwordx4 v[128:131], v[40:41], off nt
	v_add_f32_e32 v28, 1.0, v26
	v_fma_f32 v29, v19, v64, v23
	v_pk_mul_f32 v[26:27], v[6:7], v[54:55]
	v_fma_f32 v63, v20, v63, v24
	v_add_f32_e32 v26, v26, v29
	v_add_f32_e32 v29, v26, v27
	v_mul_f32_e32 v26, 0xbfb8aa3b, v29
	v_exp_f32_e32 v64, v26
	v_pk_mul_f32 v[26:27], v[30:31], v[52:53]
	v_fma_f32 v62, v21, v62, v25
	v_add_f32_e32 v26, v26, v63
	v_add_f32_e32 v63, v26, v27
	v_mul_f32_e32 v26, 0xbfb8aa3b, v63
	v_exp_f32_e32 v26, v26
	v_add_f32_e32 v27, 1.0, v64
	v_rcp_f32_e32 v64, v27
	v_rcp_f32_e32 v28, v28
	v_add_f32_e32 v26, 1.0, v26
	v_rcp_f32_e32 v66, v26
	v_pk_mul_f32 v[26:27], v[8:9], v[50:51]
	v_mul_f32_e32 v29, v29, v64
	v_add_f32_e32 v26, v26, v62
	v_add_f32_e32 v62, v26, v27
	v_mul_f32_e32 v26, 0xbfb8aa3b, v62
	v_exp_f32_e32 v26, v26
	v_fma_f32 v61, v10, v61, v14
	v_mul_f32_e32 v28, v65, v28
	v_fma_f32 v60, v11, v60, v15
	v_add_f32_e32 v26, 1.0, v26
	v_rcp_f32_e32 v64, v26
	v_pk_mul_f32 v[26:27], v[32:33], v[48:49]
	v_fma_f32 v59, v12, v59, v16
	v_add_f32_e32 v26, v26, v61
	v_add_f32_e32 v61, v26, v27
	v_mul_f32_e32 v26, 0xbfb8aa3b, v61
	v_exp_f32_e32 v65, v26
	v_pk_mul_f32 v[26:27], v[2:3], v[46:47]
	v_mul_f32_e32 v62, v62, v64
	v_add_f32_e32 v26, v26, v60
	v_add_f32_e32 v60, v26, v27
	v_mul_f32_e32 v26, 0xbfb8aa3b, v60
	v_exp_f32_e32 v26, v26
	v_add_f32_e32 v27, 1.0, v65
	v_rcp_f32_e32 v64, v27
	v_mul_f32_e32 v63, v63, v66
	v_add_f32_e32 v65, 1.0, v26
	v_pk_mul_f32 v[26:27], v[34:35], v[44:45]
	v_fma_f32 v58, v13, v58, v17
	v_add_f32_e32 v26, v26, v59
	v_add_f32_e32 v59, v26, v27
	v_mul_f32_e32 v26, 0xbfb8aa3b, v59
	v_exp_f32_e32 v66, v26
	v_pk_mul_f32 v[26:27], v[4:5], v[42:43]
	v_mul_f32_e32 v61, v61, v64
	v_add_f32_e32 v26, v26, v58
	v_add_f32_e32 v26, v26, v27
	v_mul_f32_e32 v27, 0xbfb8aa3b, v26
	v_exp_f32_e32 v27, v27
	v_rcp_f32_e32 v58, v65
	v_add_f32_e32 v65, 1.0, v66
	v_rcp_f32_e32 v65, v65
	v_add_f32_e32 v27, 1.0, v27
	v_rcp_f32_e32 v27, v27
	v_mul_f32_e32 v58, v60, v58
	v_mul_f32_e32 v59, v59, v65
	v_lshl_add_u64 v[40:41], v[40:41], 0, s[8:9]
	v_mul_f32_e32 v60, v26, v27
	v_cvt_pk_bf16_f32 v26, v28, v29
	v_cvt_pk_bf16_f32 v27, v63, v62
	v_cvt_pk_bf16_f32 v28, v61, v58
	v_cvt_pk_bf16_f32 v29, v59, v60
	global_store_dwordx4 v[38:39], v[26:29], off
	v_lshl_add_u64 v[38:39], v[38:39], 0, s[8:9]
	s_cmp_lt_i32 s6, s12
	v_mov_b32_e32 v65, v56
	v_mov_b32_e32 v64, v54
	v_mov_b32_e32 v63, v52
	v_mov_b32_e32 v62, v50
	v_mov_b32_e32 v61, v48
	v_mov_b32_e32 v60, v46
	v_mov_b32_e32 v59, v44
	v_mov_b32_e32 v58, v42
	s_cbranch_scc1 .Lcv3_0
